# prologue weight transpose: next pass loads issued before the current pass LDS read-back/stores (cross-pass prefetch)
# speedup vs baseline: 1.0022x; 1.0022x over previous
.LBB0_6:
	s_load_dwordx16 s[8:23], s[0:1], 0x0
	s_lshl_b32 s31, s4, 2
	v_mov_b32_e32 v3, v232
	s_cmpk_gt_i32 s31, 0x1a7f
	s_waitcnt lgkmcnt(0)
	v_writelane_b32 v252, s8, 1
	s_barrier
	s_nop 0
	v_writelane_b32 v252, s9, 2
	v_writelane_b32 v252, s10, 3
	v_writelane_b32 v252, s11, 4
	v_writelane_b32 v252, s12, 5
	v_writelane_b32 v252, s13, 6
	v_writelane_b32 v252, s14, 7
	v_writelane_b32 v252, s15, 8
	v_writelane_b32 v252, s16, 9
	v_writelane_b32 v252, s17, 10
	v_writelane_b32 v252, s18, 11
	v_writelane_b32 v252, s19, 12
	v_writelane_b32 v252, s20, 13
	v_writelane_b32 v252, s21, 14
	v_writelane_b32 v252, s22, 15
	v_writelane_b32 v252, s23, 16
	s_cbranch_scc1 .LBB0_498
	s_lshl_b32 s33, s62, 2
	s_add_u32 s34, s82, 0x19100000
	s_addc_u32 s35, s83, 0
	s_add_u32 s36, s82, 0x18900000
	s_addc_u32 s37, s83, 0
	v_ashrrev_i32_e32 v1, 3, v3
	v_and_b32_e32 v4, 63, v3
	v_lshlrev_b32_e32 v3, 3, v3
	s_add_u32 s38, s82, 0x17900000
	v_and_b32_e32 v2, -8, v1
	v_and_b32_e32 v6, 56, v3
	s_movk_i32 s4, 0x104
	v_or_b32_e32 v18, 7, v1
	s_addc_u32 s39, s83, 0
	v_lshl_add_u32 v7, v4, 2, 0
	v_lshl_add_u32 v8, v1, 2, 0
	v_mul_lo_u32 v9, v2, s4
	v_mul_lo_u32 v10, v18, s4
	v_mul_u32_u24_e32 v11, 0x104, v6
	s_add_u32 s40, s82, 0x16000000
	s_mov_b32 s9, 0
	v_mov_b32_e32 v5, 0
	v_or_b32_e32 v12, 1, v2
	v_or_b32_e32 v13, 2, v2
	v_or_b32_e32 v14, 3, v2
	v_or_b32_e32 v15, 4, v2
	v_or_b32_e32 v16, 5, v2
	v_or_b32_e32 v17, 6, v2
	s_addc_u32 s41, s83, 0
	v_ashrrev_i32_e32 v3, 31, v2
	s_mul_hi_i32 s42, s31, 61
	s_mul_i32 s43, s31, 61
	s_mul_i32 s61, s62, 0xf4
	s_mul_hi_i32 s64, s33, 61
	v_lshlrev_b32_e32 v4, 2, v4
	s_mov_b32 s65, 0xa040
	s_mov_b64 s[10:11], 0x3800
	s_movk_i32 s66, 0x3000
	s_movk_i32 s67, 0x1000
	s_movk_i32 s84, 0x2000
	v_lshlrev_b32_e32 v6, 1, v6
	v_add_u32_e32 v19, v7, v9
	v_add_u32_e32 v20, v7, v10
	v_add_u32_e32 v21, v8, v11
	s_mov_b32 s91, 0
	s_mov_b32 s92, 0
	s_branch .LBB0_10

.LBB0_9:
	s_add_i32 s31, s31, s33
	s_waitcnt lgkmcnt(0)
	s_barrier
	s_add_u32 s43, s43, s61
	s_addc_u32 s42, s42, s64
	s_cmpk_lt_i32 s31, 0x1a80
	s_cbranch_scc0 .LBB0_497
	v_readlane_b32 s4, v212, 16
	v_readlane_b32 s5, v212, 17
	v_readlane_b32 s6, v212, 18
	v_readlane_b32 s7, v212, 19
	v_readlane_b32 s8, v212, 20
	v_readlane_b32 s12, v212, 21
	v_readlane_b32 s13, v212, 22
	v_readlane_b32 s14, v212, 23
	v_readlane_b32 s15, v212, 24
	v_readlane_b32 s16, v212, 25
	v_readlane_b32 s17, v212, 26
	v_readlane_b32 s18, v212, 27
	v_readlane_b32 s19, v212, 28
	v_readlane_b32 s20, v212, 29
	v_readlane_b32 s60, v212, 30
	s_mov_b32 s92, 1
	s_branch .LBB0_414

.LBB0_414:
	s_cmp_eq_u32 s91, 1
	s_cbranch_scc1 .Lpro_afterA
	s_cmp_eq_u32 s90, 0
	s_cbranch_scc1 .Lpro_fl_done
	s_cmp_eq_u32 s92, 0
	s_cbranch_scc1 .Lpro_w0
	s_waitcnt vmcnt(4)
	s_branch .Lpro_w1

.Lpro_w1:
	s_bitcmp1_b32 s90, 0
	s_cbranch_scc0 .Lpro_fl_n0
	s_bitcmp1_b32 s90, 4
	s_cbranch_scc0 .Lpro_fl_w0
	v_mul_f32_e32 v64, v64, v72
	v_mul_f32_e32 v65, v65, v73
	v_mul_f32_e32 v66, v66, v74
	v_mul_f32_e32 v67, v67, v75
	v_mul_f32_e32 v68, v68, v76
	v_mul_f32_e32 v69, v69, v77
	v_mul_f32_e32 v70, v70, v78
	v_mul_f32_e32 v71, v71, v79

.Lpro_fl_n3:
.Lpro_fl_done:
	s_waitcnt lgkmcnt(0)
	s_barrier
	v_writelane_b32 v212, s4, 0
	v_writelane_b32 v212, s5, 1
	v_writelane_b32 v212, s6, 2
	v_writelane_b32 v212, s7, 3
	v_writelane_b32 v212, s8, 4
	v_writelane_b32 v212, s12, 5
	v_writelane_b32 v212, s13, 6
	v_writelane_b32 v212, s14, 7
	v_writelane_b32 v212, s15, 8
	v_writelane_b32 v212, s16, 9
	v_writelane_b32 v212, s17, 10
	v_writelane_b32 v212, s18, 11
	v_writelane_b32 v212, s19, 12
	v_writelane_b32 v212, s20, 13
	v_writelane_b32 v212, s60, 14
	s_add_i32 s31, s31, s33
	s_add_u32 s43, s43, s61
	s_addc_u32 s42, s42, s64
	s_cmpk_lt_i32 s31, 0x1a80
	s_cbranch_scc0 .Lpro_nonext
	s_mov_b32 s91, 1
	s_branch .LBB0_10
.Lpro_afterA:
	s_mov_b32 s91, 0
	v_writelane_b32 v212, s4, 16
	v_writelane_b32 v212, s5, 17
	v_writelane_b32 v212, s6, 18
	v_writelane_b32 v212, s7, 19
	v_writelane_b32 v212, s8, 20
	v_writelane_b32 v212, s12, 21
	v_writelane_b32 v212, s13, 22
	v_writelane_b32 v212, s14, 23
	v_writelane_b32 v212, s15, 24
	v_writelane_b32 v212, s16, 25
	v_writelane_b32 v212, s17, 26
	v_writelane_b32 v212, s18, 27
	v_writelane_b32 v212, s19, 28
	v_writelane_b32 v212, s20, 29
	v_writelane_b32 v212, s60, 30
	v_readlane_b32 s4, v212, 0
	v_readlane_b32 s5, v212, 1
	v_readlane_b32 s6, v212, 2
	v_readlane_b32 s7, v212, 3
	v_readlane_b32 s8, v212, 4
	v_readlane_b32 s12, v212, 5
	v_readlane_b32 s13, v212, 6
	v_readlane_b32 s14, v212, 7
	v_readlane_b32 s15, v212, 8
	v_readlane_b32 s16, v212, 9
	v_readlane_b32 s17, v212, 10
	v_readlane_b32 s18, v212, 11
	v_readlane_b32 s19, v212, 12
	v_readlane_b32 s20, v212, 13
	v_readlane_b32 s60, v212, 14
.Lpro_nonext:
	s_sub_u32 s43, s43, s61
	s_subb_u32 s42, s42, s64
	s_sub_i32 s31, s31, s33
	s_mov_b64 s[18:19], -1
	s_and_b64 vcc, exec, s[14:15]
	s_cbranch_vccz .LBB0_424
	s_and_b32 s8, s60, 0xffff
	s_cmpk_gt_u32 s8, 0xa3f
	s_mov_b64 s[14:15], -1
	s_cbranch_scc0 .LBB0_421
	s_lshl_b32 s14, s60, 6
	s_ashr_i32 s13, s12, 31
	s_cmpk_gt_u32 s8, 0xc3f
	s_mov_b64 s[6:7], -1
	s_cbranch_scc0 .LBB0_418
	s_lshl_b32 s4, s60, 2
	s_add_i32 s4, s4, 0x7fffcf00
	s_and_b32 s20, s4, 0x7fffffc0
	s_and_b32 s8, s14, 0x3c0
	s_lshl_b64 s[4:5], s[12:13], 21
	s_add_u32 s4, s34, s4
	s_addc_u32 s5, s35, s5
	s_mov_b64 s[6:7], 0
